# nt (streaming) cache policy on FFN-in HID stores and merge-gate stores; redundant acc zero-init removed
# speedup vs baseline: 1.0254x; 1.0134x over previous
; __device__ __forceinline__ u32x4 pack8(const f32x4 a, const f32x4 b) { u32x4 w; w.x = cvt_pk_bf16(a[0], a[1]); w.y = cvt_pk_bf16(a[2], a[3]); w.z = cvt_pk_bf16(b[0], b[1]); w.w = cvt_pk_bf16(b[2], b[3]); return w; }
; __device__ __forceinline__ f32x4 sigm4(const f32x4 v) { f32x4 o; o[0] = sigm(v[0]); o[1] = sigm(v[1]); o[2] = sigm(v[2]); o[3] = sigm(v[3]); return o; }
; #define EPI_ROWLOOP _Pragma("unroll") for (int ai = 0; ai < 2; ++ai) _Pragma("unroll") for (int m = 0; m < 4; ++m)
;     __device__ __forceinline__ void operator()(const f32x4 (&acc)[2][2][4][2], const Unit& u, int wr, int wc, int fr, int fq) const {
;     ...
;         } else if (pn < 26) {
;             if (u.pm * BM >= EP_MR) return;
;             const int gc = (pn - 18) * 256 + cl;
;             f32x4 bv[2][2];
; #pragma unroll
;             for (int bj = 0; bj < 2; ++bj) { bv[bj][0] = *(const f32x4*)(b_gate + gc + bj * HALF); bv[bj][1] = *(const f32x4*)(b_gate + gc + bj * HALF + 4); }
;             EPI_ROWLOOP { bf16_t* rowp = GATES + (size_t)(row0 + ai * HALF + m * 16) * 2048 + gc;
; #pragma unroll
;                 for (int bj = 0; bj < 2; ++bj) *(u32x4*)(rowp + bj * HALF) = pack8(sigm4(acc[ai][bj][m][0] + bv[bj][0]), sigm4(acc[ai][bj][m][1] + bv[bj][1])); }
.LBB0_259:
	s_andn2_b64 vcc, exec, s[0:1]
	s_cbranch_vccnz .LBB0_262
	s_cmpk_gt_i32 s48, 0xff
	s_cbranch_scc1 .LBB0_262
	v_lshl_add_u32 v170, s49, 8, v177
	v_mov_b32_e32 v171, v0
	v_lshl_add_u64 v[134:135], v[170:171], 2, s[42:43]
	global_load_dwordx4 v[138:141], v[134:135], off offset:16
	global_load_dwordx4 v[142:145], v[134:135], off
	global_load_dwordx4 v[130:133], v[134:135], off offset:528
	s_nop 0
	global_load_dwordx4 v[134:137], v[134:135], off offset:512
	v_ashrrev_i32_e32 v169, 31, v168
	v_lshlrev_b64 v[172:173], 12, v[168:169]
	v_lshl_add_u64 v[174:175], s[26:27], 0, v[172:173]
	v_lshlrev_b64 v[172:173], 1, v[170:171]
	v_lshl_add_u64 v[170:171], v[174:175], 0, v[172:173]
	s_mov_b64 s[0:1], 0x80000
	s_waitcnt vmcnt(0)
	v_pk_add_f32 v[174:175], v[128:129], v[144:145]
	s_nop 0
	v_mul_f32_e32 v174, 0xbfb8aa3b, v174
	v_exp_f32_e32 v174, v174
	v_pk_add_f32 v[182:183], v[126:127], v[142:143]
	v_add_f32_e32 v174, 1.0, v174
	v_rcp_f32_e32 v184, v174
	v_mul_f32_e32 v174, 0xbfb8aa3b, v175
	v_exp_f32_e32 v174, v174
	v_mul_f32_e32 v1, 0xbfb8aa3b, v182
	v_mul_f32_e32 v169, 0xbfb8aa3b, v183
	v_pk_add_f32 v[182:183], v[122:123], v[138:139]
	v_add_f32_e32 v174, 1.0, v174
	v_rcp_f32_e32 v185, v174
	v_pk_add_f32 v[174:175], v[124:125], v[140:141]
	v_mul_f32_e32 v182, 0xbfb8aa3b, v182
	v_exp_f32_e32 v182, v182
	v_mul_f32_e32 v174, 0xbfb8aa3b, v174
	v_mul_f32_e32 v175, 0xbfb8aa3b, v175
	v_exp_f32_e32 v174, v174
	v_exp_f32_e32 v175, v175
	v_add_f32_e32 v182, 1.0, v182
	v_rcp_f32_e32 v186, v182
	v_mul_f32_e32 v182, 0xbfb8aa3b, v183
	v_add_f32_e32 v174, 1.0, v174
	v_add_f32_e32 v175, 1.0, v175
	v_exp_f32_e32 v1, v1
	v_exp_f32_e32 v169, v169
	v_exp_f32_e32 v182, v182
	v_rcp_f32_e32 v174, v174
	v_rcp_f32_e32 v175, v175
	v_add_f32_e32 v1, 1.0, v1
	v_add_f32_e32 v169, 1.0, v169
	v_add_f32_e32 v182, 1.0, v182
	v_cvt_pk_bf16_f32 v183, v184, v185
	v_cvt_pk_bf16_f32 v185, v174, v175
	v_pk_add_f32 v[174:175], v[120:121], v[136:137]
	v_rcp_f32_e32 v1, v1
	v_rcp_f32_e32 v169, v169
	v_rcp_f32_e32 v187, v182
	v_mul_f32_e32 v174, 0xbfb8aa3b, v174
	v_exp_f32_e32 v174, v174
	v_cvt_pk_bf16_f32 v182, v1, v169
	v_cvt_pk_bf16_f32 v184, v186, v187
	global_store_dwordx4 v[170:171], v[182:185], off nt
	v_add_f32_e32 v174, 1.0, v174
	s_nop 0
	v_pk_add_f32 v[182:183], v[118:119], v[134:135]
	v_rcp_f32_e32 v184, v174
	v_mul_f32_e32 v1, 0xbfb8aa3b, v182
	v_mul_f32_e32 v169, 0xbfb8aa3b, v183
	v_mul_f32_e32 v174, 0xbfb8aa3b, v175
	v_pk_add_f32 v[182:183], v[114:115], v[130:131]
	v_exp_f32_e32 v174, v174
	v_mul_f32_e32 v182, 0xbfb8aa3b, v182
	v_exp_f32_e32 v182, v182
	v_exp_f32_e32 v1, v1
	v_add_f32_e32 v174, 1.0, v174
	v_rcp_f32_e32 v185, v174
	v_pk_add_f32 v[174:175], v[116:117], v[132:133]
	v_add_f32_e32 v182, 1.0, v182
	v_rcp_f32_e32 v186, v182
	v_mul_f32_e32 v182, 0xbfb8aa3b, v183
	v_mul_f32_e32 v174, 0xbfb8aa3b, v174
	v_mul_f32_e32 v175, 0xbfb8aa3b, v175
	v_exp_f32_e32 v169, v169
	v_exp_f32_e32 v182, v182
	v_exp_f32_e32 v174, v174
	v_exp_f32_e32 v175, v175
	v_add_f32_e32 v1, 1.0, v1
	v_add_f32_e32 v169, 1.0, v169
	v_add_f32_e32 v182, 1.0, v182
	v_add_f32_e32 v174, 1.0, v174
	v_add_f32_e32 v175, 1.0, v175
	v_rcp_f32_e32 v1, v1
	v_rcp_f32_e32 v169, v169
	v_rcp_f32_e32 v187, v182
	v_rcp_f32_e32 v174, v174
	v_rcp_f32_e32 v175, v175
	v_cvt_pk_bf16_f32 v182, v1, v169
	v_cvt_pk_bf16_f32 v183, v184, v185
	v_cvt_pk_bf16_f32 v184, v186, v187
	v_cvt_pk_bf16_f32 v185, v174, v175
	global_store_dwordx4 v[170:171], v[182:185], off offset:256 nt
	v_or_b32_e32 v174, 16, v168
	v_ashrrev_i32_e32 v175, 31, v174
	v_pk_add_f32 v[182:183], v[112:113], v[144:145]
	v_pk_add_f32 v[184:185], v[110:111], v[142:143]
	v_mul_f32_e32 v182, 0xbfb8aa3b, v182
	v_exp_f32_e32 v182, v182
	v_mul_f32_e32 v1, 0xbfb8aa3b, v184
	v_mul_f32_e32 v169, 0xbfb8aa3b, v185
	v_pk_add_f32 v[184:185], v[106:107], v[138:139]
	v_add_f32_e32 v182, 1.0, v182
	v_rcp_f32_e32 v186, v182
	v_mul_f32_e32 v182, 0xbfb8aa3b, v183
	v_exp_f32_e32 v182, v182
	v_mul_f32_e32 v184, 0xbfb8aa3b, v184
	v_mul_f32_e32 v185, 0xbfb8aa3b, v185
	v_exp_f32_e32 v1, v1
	v_add_f32_e32 v182, 1.0, v182
	v_rcp_f32_e32 v187, v182
	v_pk_add_f32 v[182:183], v[108:109], v[140:141]
	v_exp_f32_e32 v169, v169
	v_mul_f32_e32 v182, 0xbfb8aa3b, v182
	v_exp_f32_e32 v182, v182
	v_exp_f32_e32 v184, v184
	v_exp_f32_e32 v185, v185
	v_add_f32_e32 v1, 1.0, v1
	v_add_f32_e32 v182, 1.0, v182
	v_rcp_f32_e32 v188, v182
	v_mul_f32_e32 v182, 0xbfb8aa3b, v183
	v_exp_f32_e32 v182, v182
	v_add_f32_e32 v169, 1.0, v169
	v_add_f32_e32 v184, 1.0, v184
	v_add_f32_e32 v185, 1.0, v185
	v_add_f32_e32 v182, 1.0, v182
	v_rcp_f32_e32 v1, v1
	v_rcp_f32_e32 v169, v169
	v_rcp_f32_e32 v184, v184
	v_rcp_f32_e32 v185, v185
	v_rcp_f32_e32 v189, v182
	v_lshlrev_b64 v[174:175], 12, v[174:175]
	v_lshl_add_u64 v[174:175], s[26:27], 0, v[174:175]
	v_lshl_add_u64 v[174:175], v[174:175], 0, v[172:173]
	v_cvt_pk_bf16_f32 v182, v1, v169
	v_cvt_pk_bf16_f32 v183, v186, v187
	v_cvt_pk_bf16_f32 v184, v184, v185
	v_cvt_pk_bf16_f32 v185, v188, v189
	global_store_dwordx4 v[174:175], v[182:185], off nt
	s_nop 1
	v_pk_add_f32 v[182:183], v[104:105], v[136:137]
	v_pk_add_f32 v[184:185], v[102:103], v[134:135]
	v_mul_f32_e32 v182, 0xbfb8aa3b, v182
	v_exp_f32_e32 v182, v182
	v_mul_f32_e32 v1, 0xbfb8aa3b, v184
	v_mul_f32_e32 v169, 0xbfb8aa3b, v185
	v_pk_add_f32 v[184:185], v[98:99], v[130:131]
	v_add_f32_e32 v182, 1.0, v182
	v_rcp_f32_e32 v186, v182
	v_mul_f32_e32 v182, 0xbfb8aa3b, v183
	v_exp_f32_e32 v182, v182
	v_mul_f32_e32 v184, 0xbfb8aa3b, v184
	v_mul_f32_e32 v185, 0xbfb8aa3b, v185
	v_exp_f32_e32 v1, v1
	v_add_f32_e32 v182, 1.0, v182
	v_rcp_f32_e32 v187, v182
	v_pk_add_f32 v[182:183], v[100:101], v[132:133]
; __device__ __forceinline__ u32x4 pack8(const f32x4 a, const f32x4 b) { u32x4 w; w.x = cvt_pk_bf16(a[0], a[1]); w.y = cvt_pk_bf16(a[2], a[3]); w.z = cvt_pk_bf16(b[0], b[1]); w.w = cvt_pk_bf16(b[2], b[3]); return w; }
; __device__ __forceinline__ f32x4 sigm4(const f32x4 v) { f32x4 o; o[0] = sigm(v[0]); o[1] = sigm(v[1]); o[2] = sigm(v[2]); o[3] = sigm(v[3]); return o; }
; #define EPI_ROWLOOP _Pragma("unroll") for (int ai = 0; ai < 2; ++ai) _Pragma("unroll") for (int m = 0; m < 4; ++m)
;     __device__ __forceinline__ void operator()(const f32x4 (&acc)[2][2][4][2], const Unit& u, int wr, int wc, int fr, int fq) const {
;     ...
;         } else if (pn < 26) {
;             if (u.pm * BM >= EP_MR) return;
;             const int gc = (pn - 18) * 256 + cl;
;             f32x4 bv[2][2];
; #pragma unroll
;             for (int bj = 0; bj < 2; ++bj) { bv[bj][0] = *(const f32x4*)(b_gate + gc + bj * HALF); bv[bj][1] = *(const f32x4*)(b_gate + gc + bj * HALF + 4); }
;             EPI_ROWLOOP { bf16_t* rowp = GATES + (size_t)(row0 + ai * HALF + m * 16) * 2048 + gc;
; #pragma unroll
;                 for (int bj = 0; bj < 2; ++bj) *(u32x4*)(rowp + bj * HALF) = pack8(sigm4(acc[ai][bj][m][0] + bv[bj][0]), sigm4(acc[ai][bj][m][1] + bv[bj][1])); }
	v_exp_f32_e32 v169, v169
	v_mul_f32_e32 v182, 0xbfb8aa3b, v182
	v_exp_f32_e32 v182, v182
	v_exp_f32_e32 v184, v184
	v_exp_f32_e32 v185, v185
	v_add_f32_e32 v1, 1.0, v1
	v_add_f32_e32 v182, 1.0, v182
	v_rcp_f32_e32 v188, v182
	v_mul_f32_e32 v182, 0xbfb8aa3b, v183
	v_exp_f32_e32 v182, v182
	v_add_f32_e32 v169, 1.0, v169
	v_add_f32_e32 v184, 1.0, v184
	v_add_f32_e32 v185, 1.0, v185
	v_add_f32_e32 v182, 1.0, v182
	v_rcp_f32_e32 v1, v1
	v_rcp_f32_e32 v169, v169
	v_rcp_f32_e32 v184, v184
	v_rcp_f32_e32 v185, v185
	v_rcp_f32_e32 v189, v182
	v_cvt_pk_bf16_f32 v182, v1, v169
	v_cvt_pk_bf16_f32 v183, v186, v187
	v_cvt_pk_bf16_f32 v184, v184, v185
	v_cvt_pk_bf16_f32 v185, v188, v189
	global_store_dwordx4 v[174:175], v[182:185], off offset:256 nt
	v_or_b32_e32 v174, 32, v168
	v_ashrrev_i32_e32 v175, 31, v174
	v_pk_add_f32 v[182:183], v[96:97], v[144:145]
	v_pk_add_f32 v[184:185], v[94:95], v[142:143]
	v_mul_f32_e32 v182, 0xbfb8aa3b, v182
	v_exp_f32_e32 v182, v182
	v_mul_f32_e32 v1, 0xbfb8aa3b, v184
	v_mul_f32_e32 v169, 0xbfb8aa3b, v185
	v_pk_add_f32 v[184:185], v[90:91], v[138:139]
	v_add_f32_e32 v182, 1.0, v182
	v_rcp_f32_e32 v186, v182
	v_mul_f32_e32 v182, 0xbfb8aa3b, v183
	v_exp_f32_e32 v182, v182
	v_mul_f32_e32 v184, 0xbfb8aa3b, v184
	v_mul_f32_e32 v185, 0xbfb8aa3b, v185
	v_exp_f32_e32 v1, v1
	v_add_f32_e32 v182, 1.0, v182
	v_rcp_f32_e32 v187, v182
	v_pk_add_f32 v[182:183], v[92:93], v[140:141]
	v_exp_f32_e32 v169, v169
	v_mul_f32_e32 v182, 0xbfb8aa3b, v182
	v_exp_f32_e32 v182, v182
	v_exp_f32_e32 v184, v184
	v_exp_f32_e32 v185, v185
	v_add_f32_e32 v1, 1.0, v1
	v_add_f32_e32 v182, 1.0, v182
	v_rcp_f32_e32 v188, v182
	v_mul_f32_e32 v182, 0xbfb8aa3b, v183
	v_exp_f32_e32 v182, v182
	v_add_f32_e32 v169, 1.0, v169
	v_add_f32_e32 v184, 1.0, v184
	v_add_f32_e32 v185, 1.0, v185
	v_add_f32_e32 v182, 1.0, v182
	v_rcp_f32_e32 v1, v1
	v_rcp_f32_e32 v169, v169
	v_rcp_f32_e32 v184, v184
	v_rcp_f32_e32 v185, v185
	v_rcp_f32_e32 v189, v182
	v_lshlrev_b64 v[174:175], 12, v[174:175]
	v_lshl_add_u64 v[174:175], s[26:27], 0, v[174:175]
	v_lshl_add_u64 v[174:175], v[174:175], 0, v[172:173]
	v_cvt_pk_bf16_f32 v182, v1, v169
	v_cvt_pk_bf16_f32 v183, v186, v187
	v_cvt_pk_bf16_f32 v184, v184, v185
	v_cvt_pk_bf16_f32 v185, v188, v189
	global_store_dwordx4 v[174:175], v[182:185], off nt
	s_nop 1
	v_pk_add_f32 v[182:183], v[88:89], v[136:137]
	v_pk_add_f32 v[184:185], v[86:87], v[134:135]
	v_mul_f32_e32 v182, 0xbfb8aa3b, v182
	v_exp_f32_e32 v182, v182
	v_mul_f32_e32 v1, 0xbfb8aa3b, v184
	v_mul_f32_e32 v169, 0xbfb8aa3b, v185
	v_pk_add_f32 v[184:185], v[82:83], v[130:131]
	v_add_f32_e32 v182, 1.0, v182
	v_rcp_f32_e32 v186, v182
	v_mul_f32_e32 v182, 0xbfb8aa3b, v183
	v_exp_f32_e32 v182, v182
	v_mul_f32_e32 v184, 0xbfb8aa3b, v184
	v_mul_f32_e32 v185, 0xbfb8aa3b, v185
	v_exp_f32_e32 v1, v1
	v_add_f32_e32 v182, 1.0, v182
	v_rcp_f32_e32 v187, v182
	v_pk_add_f32 v[182:183], v[84:85], v[132:133]
	v_exp_f32_e32 v169, v169
	v_mul_f32_e32 v182, 0xbfb8aa3b, v182
	v_exp_f32_e32 v182, v182
	v_exp_f32_e32 v184, v184
	v_exp_f32_e32 v185, v185
	v_add_f32_e32 v1, 1.0, v1
	v_add_f32_e32 v182, 1.0, v182
	v_rcp_f32_e32 v188, v182
	v_mul_f32_e32 v182, 0xbfb8aa3b, v183
	v_exp_f32_e32 v182, v182
	v_add_f32_e32 v169, 1.0, v169
	v_add_f32_e32 v184, 1.0, v184
	v_add_f32_e32 v185, 1.0, v185
	v_add_f32_e32 v182, 1.0, v182
	v_rcp_f32_e32 v1, v1
	v_rcp_f32_e32 v169, v169
	v_rcp_f32_e32 v184, v184
	v_rcp_f32_e32 v185, v185
	v_rcp_f32_e32 v189, v182
	v_cvt_pk_bf16_f32 v182, v1, v169
	v_cvt_pk_bf16_f32 v183, v186, v187
	v_cvt_pk_bf16_f32 v184, v184, v185
	v_cvt_pk_bf16_f32 v185, v188, v189
	global_store_dwordx4 v[174:175], v[182:185], off offset:256 nt
	v_or_b32_e32 v174, 48, v168
	v_ashrrev_i32_e32 v175, 31, v174
	v_lshlrev_b64 v[174:175], 12, v[174:175]
	v_lshl_add_u64 v[174:175], s[26:27], 0, v[174:175]
	v_lshl_add_u64 v[172:173], v[174:175], 0, v[172:173]
	v_pk_add_f32 v[174:175], v[80:81], v[144:145]
	v_pk_add_f32 v[182:183], v[78:79], v[142:143]
	v_mul_f32_e32 v174, 0xbfb8aa3b, v174
	v_exp_f32_e32 v174, v174
	v_mul_f32_e32 v1, 0xbfb8aa3b, v182
	v_mul_f32_e32 v169, 0xbfb8aa3b, v183
	v_pk_add_f32 v[182:183], v[74:75], v[138:139]
	v_add_f32_e32 v174, 1.0, v174
	v_rcp_f32_e32 v184, v174
	v_mul_f32_e32 v174, 0xbfb8aa3b, v175
	v_exp_f32_e32 v174, v174
	v_mul_f32_e32 v182, 0xbfb8aa3b, v182
	v_exp_f32_e32 v182, v182
	v_exp_f32_e32 v1, v1
	v_add_f32_e32 v174, 1.0, v174
	v_rcp_f32_e32 v185, v174
	v_pk_add_f32 v[174:175], v[76:77], v[140:141]
	v_add_f32_e32 v182, 1.0, v182
	v_mul_f32_e32 v174, 0xbfb8aa3b, v174
	v_mul_f32_e32 v175, 0xbfb8aa3b, v175
	v_exp_f32_e32 v174, v174
	v_exp_f32_e32 v175, v175
	v_rcp_f32_e32 v186, v182
	v_mul_f32_e32 v182, 0xbfb8aa3b, v183
	v_add_f32_e32 v174, 1.0, v174
	v_add_f32_e32 v175, 1.0, v175
	v_rcp_f32_e32 v174, v174
	v_rcp_f32_e32 v175, v175
	v_exp_f32_e32 v169, v169
	v_exp_f32_e32 v182, v182
	v_cvt_pk_bf16_f32 v183, v184, v185
	v_cvt_pk_bf16_f32 v185, v174, v175
	v_pk_add_f32 v[174:175], v[72:73], v[136:137]
	v_add_f32_e32 v1, 1.0, v1
	v_add_f32_e32 v169, 1.0, v169
	v_add_f32_e32 v182, 1.0, v182
	v_mul_f32_e32 v174, 0xbfb8aa3b, v174
	v_rcp_f32_e32 v1, v1
	v_rcp_f32_e32 v169, v169
	v_rcp_f32_e32 v187, v182
	v_exp_f32_e32 v174, v174
	v_cvt_pk_bf16_f32 v182, v1, v169
	v_cvt_pk_bf16_f32 v184, v186, v187
	v_add_f32_e32 v174, 1.0, v174
	global_store_dwordx4 v[172:173], v[182:185], off nt
	s_nop 1
	v_rcp_f32_e32 v184, v174
	v_mul_f32_e32 v174, 0xbfb8aa3b, v175
	v_exp_f32_e32 v174, v174
	v_pk_add_f32 v[182:183], v[70:71], v[134:135]
	v_add_f32_e32 v174, 1.0, v174
	v_mul_f32_e32 v1, 0xbfb8aa3b, v182
	v_mul_f32_e32 v169, 0xbfb8aa3b, v183
	v_rcp_f32_e32 v185, v174
; __device__ __forceinline__ u32x4 pack8(const f32x4 a, const f32x4 b) { u32x4 w; w.x = cvt_pk_bf16(a[0], a[1]); w.y = cvt_pk_bf16(a[2], a[3]); w.z = cvt_pk_bf16(b[0], b[1]); w.w = cvt_pk_bf16(b[2], b[3]); return w; }
; __device__ __forceinline__ f32x4 sigm4(const f32x4 v) { f32x4 o; o[0] = sigm(v[0]); o[1] = sigm(v[1]); o[2] = sigm(v[2]); o[3] = sigm(v[3]); return o; }
; #define EPI_ROWLOOP _Pragma("unroll") for (int ai = 0; ai < 2; ++ai) _Pragma("unroll") for (int m = 0; m < 4; ++m)
;     __device__ __forceinline__ void operator()(const f32x4 (&acc)[2][2][4][2], const Unit& u, int wr, int wc, int fr, int fq) const {
;     ...
;         } else if (pn < 26) {
;             if (u.pm * BM >= EP_MR) return;
;             const int gc = (pn - 18) * 256 + cl;
;             f32x4 bv[2][2];
; #pragma unroll
;             for (int bj = 0; bj < 2; ++bj) { bv[bj][0] = *(const f32x4*)(b_gate + gc + bj * HALF); bv[bj][1] = *(const f32x4*)(b_gate + gc + bj * HALF + 4); }
;             EPI_ROWLOOP { bf16_t* rowp = GATES + (size_t)(row0 + ai * HALF + m * 16) * 2048 + gc;
; #pragma unroll
;                 for (int bj = 0; bj < 2; ++bj) *(u32x4*)(rowp + bj * HALF) = pack8(sigm4(acc[ai][bj][m][0] + bv[bj][0]), sigm4(acc[ai][bj][m][1] + bv[bj][1])); }
	v_pk_add_f32 v[174:175], v[68:69], v[132:133]
	v_pk_add_f32 v[182:183], v[66:67], v[130:131]
	v_mul_f32_e32 v174, 0xbfb8aa3b, v174
	v_mul_f32_e32 v182, 0xbfb8aa3b, v182
	v_mul_f32_e32 v175, 0xbfb8aa3b, v175
	v_exp_f32_e32 v182, v182
	v_exp_f32_e32 v174, v174
	v_exp_f32_e32 v175, v175
	v_exp_f32_e32 v1, v1
	v_add_f32_e32 v182, 1.0, v182
	v_add_f32_e32 v174, 1.0, v174
	v_add_f32_e32 v175, 1.0, v175
	v_rcp_f32_e32 v186, v182
	v_mul_f32_e32 v182, 0xbfb8aa3b, v183
	v_rcp_f32_e32 v174, v174
	v_rcp_f32_e32 v175, v175
	v_exp_f32_e32 v169, v169
	v_exp_f32_e32 v182, v182
	v_cvt_pk_bf16_f32 v183, v184, v185
	v_cvt_pk_bf16_f32 v185, v174, v175
	v_pk_add_f32 v[174:175], v[64:65], v[144:145]
	v_add_f32_e32 v1, 1.0, v1
	v_add_f32_e32 v169, 1.0, v169
	v_add_f32_e32 v182, 1.0, v182
	v_mul_f32_e32 v174, 0xbfb8aa3b, v174
	v_rcp_f32_e32 v1, v1
	v_rcp_f32_e32 v169, v169
	v_rcp_f32_e32 v187, v182
	v_exp_f32_e32 v174, v174
	v_cvt_pk_bf16_f32 v182, v1, v169
	v_cvt_pk_bf16_f32 v184, v186, v187
	v_add_f32_e32 v174, 1.0, v174
	global_store_dwordx4 v[172:173], v[182:185], off offset:256 nt
	v_lshl_add_u64 v[172:173], v[170:171], 0, s[0:1]
	s_mov_b32 s0, 0x80000
	v_pk_add_f32 v[182:183], v[62:63], v[142:143]
	v_rcp_f32_e32 v184, v174
	v_mul_f32_e32 v174, 0xbfb8aa3b, v175
	v_mul_f32_e32 v1, 0xbfb8aa3b, v182
	v_mul_f32_e32 v169, 0xbfb8aa3b, v183
	v_exp_f32_e32 v174, v174
	v_pk_add_f32 v[182:183], v[58:59], v[138:139]
	v_exp_f32_e32 v1, v1
	v_mul_f32_e32 v182, 0xbfb8aa3b, v182
	v_exp_f32_e32 v182, v182
	v_add_f32_e32 v174, 1.0, v174
	v_rcp_f32_e32 v185, v174
	v_pk_add_f32 v[174:175], v[60:61], v[140:141]
	v_add_f32_e32 v182, 1.0, v182
	v_mul_f32_e32 v174, 0xbfb8aa3b, v174
	v_mul_f32_e32 v175, 0xbfb8aa3b, v175
	v_rcp_f32_e32 v186, v182
	v_mul_f32_e32 v182, 0xbfb8aa3b, v183
	v_exp_f32_e32 v174, v174
	v_exp_f32_e32 v175, v175
	v_exp_f32_e32 v169, v169
	v_exp_f32_e32 v182, v182
	v_add_f32_e32 v174, 1.0, v174
	v_add_f32_e32 v175, 1.0, v175
	v_add_f32_e32 v1, 1.0, v1
	v_add_f32_e32 v169, 1.0, v169
	v_add_f32_e32 v182, 1.0, v182
	v_rcp_f32_e32 v174, v174
	v_rcp_f32_e32 v175, v175
	v_rcp_f32_e32 v1, v1
	v_rcp_f32_e32 v169, v169
	v_rcp_f32_e32 v187, v182
	v_cvt_pk_bf16_f32 v183, v184, v185
	v_cvt_pk_bf16_f32 v185, v174, v175
	v_add_co_u32_e32 v174, vcc, s0, v170
	v_cvt_pk_bf16_f32 v182, v1, v169
	v_cvt_pk_bf16_f32 v184, v186, v187
	v_addc_co_u32_e32 v175, vcc, 0, v171, vcc
	global_store_dwordx4 v[174:175], v[182:185], off nt
	v_pk_add_f32 v[174:175], v[56:57], v[136:137]
	s_mov_b64 s[0:1], 0x90000
	v_mul_f32_e32 v174, 0xbfb8aa3b, v174
	v_exp_f32_e32 v174, v174
	v_pk_add_f32 v[182:183], v[54:55], v[134:135]
	v_add_f32_e32 v174, 1.0, v174
	v_rcp_f32_e32 v184, v174
	v_mul_f32_e32 v174, 0xbfb8aa3b, v175
	v_exp_f32_e32 v174, v174
	v_mul_f32_e32 v1, 0xbfb8aa3b, v182
	v_mul_f32_e32 v169, 0xbfb8aa3b, v183
	v_pk_add_f32 v[182:183], v[50:51], v[130:131]
	v_add_f32_e32 v174, 1.0, v174
	v_rcp_f32_e32 v185, v174
	v_pk_add_f32 v[174:175], v[52:53], v[132:133]
	v_mul_f32_e32 v182, 0xbfb8aa3b, v182
	v_mul_f32_e32 v174, 0xbfb8aa3b, v174
	v_mul_f32_e32 v175, 0xbfb8aa3b, v175
	v_exp_f32_e32 v182, v182
	v_exp_f32_e32 v174, v174
	v_exp_f32_e32 v175, v175
	v_exp_f32_e32 v1, v1
	v_add_f32_e32 v182, 1.0, v182
	v_add_f32_e32 v174, 1.0, v174
	v_add_f32_e32 v175, 1.0, v175
	v_rcp_f32_e32 v186, v182
	v_mul_f32_e32 v182, 0xbfb8aa3b, v183
	v_rcp_f32_e32 v174, v174
	v_rcp_f32_e32 v175, v175
	v_exp_f32_e32 v169, v169
	v_exp_f32_e32 v182, v182
	v_cvt_pk_bf16_f32 v183, v184, v185
	v_cvt_pk_bf16_f32 v185, v174, v175
	v_pk_add_f32 v[174:175], v[48:49], v[144:145]
	v_add_f32_e32 v1, 1.0, v1
	v_add_f32_e32 v169, 1.0, v169
	v_add_f32_e32 v182, 1.0, v182
	v_mul_f32_e32 v174, 0xbfb8aa3b, v174
	v_rcp_f32_e32 v1, v1
	v_rcp_f32_e32 v169, v169
	v_rcp_f32_e32 v187, v182
	v_exp_f32_e32 v174, v174
	v_cvt_pk_bf16_f32 v182, v1, v169
	v_cvt_pk_bf16_f32 v184, v186, v187
	v_add_f32_e32 v174, 1.0, v174
	global_store_dwordx4 v[172:173], v[182:185], off offset:256 nt
	v_lshl_add_u64 v[172:173], v[170:171], 0, s[0:1]
	s_mov_b32 s0, 0x90000
	v_pk_add_f32 v[182:183], v[46:47], v[142:143]
	v_rcp_f32_e32 v184, v174
	v_mul_f32_e32 v174, 0xbfb8aa3b, v175
	v_mul_f32_e32 v1, 0xbfb8aa3b, v182
	v_mul_f32_e32 v169, 0xbfb8aa3b, v183
	v_exp_f32_e32 v174, v174
	v_pk_add_f32 v[182:183], v[42:43], v[138:139]
	v_exp_f32_e32 v1, v1
	v_mul_f32_e32 v182, 0xbfb8aa3b, v182
	v_exp_f32_e32 v182, v182
	v_add_f32_e32 v174, 1.0, v174
	v_rcp_f32_e32 v185, v174
	v_pk_add_f32 v[174:175], v[44:45], v[140:141]
	v_add_f32_e32 v182, 1.0, v182
	v_mul_f32_e32 v174, 0xbfb8aa3b, v174
	v_mul_f32_e32 v175, 0xbfb8aa3b, v175
	v_rcp_f32_e32 v186, v182
	v_mul_f32_e32 v182, 0xbfb8aa3b, v183
	v_exp_f32_e32 v174, v174
	v_exp_f32_e32 v175, v175
	v_exp_f32_e32 v169, v169
	v_exp_f32_e32 v182, v182
	v_add_f32_e32 v174, 1.0, v174
	v_add_f32_e32 v175, 1.0, v175
	v_add_f32_e32 v1, 1.0, v1
	v_add_f32_e32 v169, 1.0, v169
	v_add_f32_e32 v182, 1.0, v182
	v_rcp_f32_e32 v174, v174
	v_rcp_f32_e32 v175, v175
	v_rcp_f32_e32 v1, v1
	v_rcp_f32_e32 v169, v169
	v_rcp_f32_e32 v187, v182
	v_cvt_pk_bf16_f32 v183, v184, v185
	v_cvt_pk_bf16_f32 v185, v174, v175
	v_add_co_u32_e32 v174, vcc, s0, v170
	v_cvt_pk_bf16_f32 v182, v1, v169
	v_cvt_pk_bf16_f32 v184, v186, v187
	v_addc_co_u32_e32 v175, vcc, 0, v171, vcc
	global_store_dwordx4 v[174:175], v[182:185], off nt
	v_pk_add_f32 v[174:175], v[40:41], v[136:137]
	s_mov_b64 s[0:1], 0xa0000
	v_mul_f32_e32 v174, 0xbfb8aa3b, v174
	v_exp_f32_e32 v174, v174
	v_pk_add_f32 v[182:183], v[38:39], v[134:135]
	v_add_f32_e32 v174, 1.0, v174
	v_rcp_f32_e32 v184, v174
	v_mul_f32_e32 v174, 0xbfb8aa3b, v175
	v_exp_f32_e32 v174, v174
	v_mul_f32_e32 v1, 0xbfb8aa3b, v182
; __device__ __forceinline__ u32x4 pack8(const f32x4 a, const f32x4 b) { u32x4 w; w.x = cvt_pk_bf16(a[0], a[1]); w.y = cvt_pk_bf16(a[2], a[3]); w.z = cvt_pk_bf16(b[0], b[1]); w.w = cvt_pk_bf16(b[2], b[3]); return w; }
; __device__ __forceinline__ f32x4 sigm4(const f32x4 v) { f32x4 o; o[0] = sigm(v[0]); o[1] = sigm(v[1]); o[2] = sigm(v[2]); o[3] = sigm(v[3]); return o; }
; #define EPI_ROWLOOP _Pragma("unroll") for (int ai = 0; ai < 2; ++ai) _Pragma("unroll") for (int m = 0; m < 4; ++m)
;     __device__ __forceinline__ void operator()(const f32x4 (&acc)[2][2][4][2], const Unit& u, int wr, int wc, int fr, int fq) const {
;     ...
;         } else if (pn < 26) {
;             if (u.pm * BM >= EP_MR) return;
;             const int gc = (pn - 18) * 256 + cl;
;             f32x4 bv[2][2];
; #pragma unroll
;             for (int bj = 0; bj < 2; ++bj) { bv[bj][0] = *(const f32x4*)(b_gate + gc + bj * HALF); bv[bj][1] = *(const f32x4*)(b_gate + gc + bj * HALF + 4); }
;             EPI_ROWLOOP { bf16_t* rowp = GATES + (size_t)(row0 + ai * HALF + m * 16) * 2048 + gc;
; #pragma unroll
;                 for (int bj = 0; bj < 2; ++bj) *(u32x4*)(rowp + bj * HALF) = pack8(sigm4(acc[ai][bj][m][0] + bv[bj][0]), sigm4(acc[ai][bj][m][1] + bv[bj][1])); }
	v_mul_f32_e32 v169, 0xbfb8aa3b, v183
	v_pk_add_f32 v[182:183], v[34:35], v[130:131]
	v_add_f32_e32 v174, 1.0, v174
	v_rcp_f32_e32 v185, v174
	v_pk_add_f32 v[174:175], v[36:37], v[132:133]
	v_mul_f32_e32 v182, 0xbfb8aa3b, v182
	v_mul_f32_e32 v174, 0xbfb8aa3b, v174
	v_mul_f32_e32 v175, 0xbfb8aa3b, v175
	v_exp_f32_e32 v182, v182
	v_exp_f32_e32 v174, v174
	v_exp_f32_e32 v175, v175
	v_exp_f32_e32 v1, v1
	v_add_f32_e32 v182, 1.0, v182
	v_add_f32_e32 v174, 1.0, v174
	v_add_f32_e32 v175, 1.0, v175
	v_rcp_f32_e32 v186, v182
	v_mul_f32_e32 v182, 0xbfb8aa3b, v183
	v_rcp_f32_e32 v174, v174
	v_rcp_f32_e32 v175, v175
	v_exp_f32_e32 v169, v169
	v_exp_f32_e32 v182, v182
	v_cvt_pk_bf16_f32 v183, v184, v185
	v_cvt_pk_bf16_f32 v185, v174, v175
	v_pk_add_f32 v[174:175], v[32:33], v[144:145]
	v_add_f32_e32 v1, 1.0, v1
	v_add_f32_e32 v169, 1.0, v169
	v_add_f32_e32 v182, 1.0, v182
	v_mul_f32_e32 v174, 0xbfb8aa3b, v174
	v_rcp_f32_e32 v1, v1
	v_rcp_f32_e32 v169, v169
	v_rcp_f32_e32 v187, v182
	v_exp_f32_e32 v174, v174
	v_pk_add_f32 v[144:145], v[16:17], v[144:145]
	v_cvt_pk_bf16_f32 v182, v1, v169
	v_cvt_pk_bf16_f32 v184, v186, v187
	v_add_f32_e32 v174, 1.0, v174
	global_store_dwordx4 v[172:173], v[182:185], off offset:256 nt
	v_lshl_add_u64 v[172:173], v[170:171], 0, s[0:1]
	s_mov_b32 s0, 0xa0000
	v_pk_add_f32 v[182:183], v[30:31], v[142:143]
	v_rcp_f32_e32 v184, v174
	v_mul_f32_e32 v174, 0xbfb8aa3b, v175
	v_mul_f32_e32 v1, 0xbfb8aa3b, v182
	v_mul_f32_e32 v169, 0xbfb8aa3b, v183
	v_exp_f32_e32 v174, v174
	v_pk_add_f32 v[182:183], v[26:27], v[138:139]
	v_exp_f32_e32 v1, v1
	v_mul_f32_e32 v182, 0xbfb8aa3b, v182
	v_exp_f32_e32 v182, v182
	v_add_f32_e32 v174, 1.0, v174
	v_rcp_f32_e32 v185, v174
	v_pk_add_f32 v[174:175], v[28:29], v[140:141]
	v_add_f32_e32 v182, 1.0, v182
	v_mul_f32_e32 v174, 0xbfb8aa3b, v174
	v_mul_f32_e32 v175, 0xbfb8aa3b, v175
	v_rcp_f32_e32 v186, v182
	v_mul_f32_e32 v182, 0xbfb8aa3b, v183
	v_exp_f32_e32 v174, v174
	v_exp_f32_e32 v175, v175
	v_exp_f32_e32 v169, v169
	v_exp_f32_e32 v182, v182
	v_add_f32_e32 v174, 1.0, v174
	v_add_f32_e32 v175, 1.0, v175
	v_add_f32_e32 v1, 1.0, v1
	v_add_f32_e32 v169, 1.0, v169
	v_add_f32_e32 v182, 1.0, v182
	v_rcp_f32_e32 v174, v174
	v_rcp_f32_e32 v175, v175
	v_rcp_f32_e32 v1, v1
	v_rcp_f32_e32 v169, v169
	v_rcp_f32_e32 v187, v182
	v_cvt_pk_bf16_f32 v183, v184, v185
	v_cvt_pk_bf16_f32 v185, v174, v175
	v_add_co_u32_e32 v174, vcc, s0, v170
	v_cvt_pk_bf16_f32 v182, v1, v169
	v_cvt_pk_bf16_f32 v184, v186, v187
	v_addc_co_u32_e32 v175, vcc, 0, v171, vcc
	global_store_dwordx4 v[174:175], v[182:185], off nt
	v_pk_add_f32 v[174:175], v[24:25], v[136:137]
	v_pk_add_f32 v[138:139], v[10:11], v[138:139]
	v_pk_add_f32 v[182:183], v[22:23], v[134:135]
	v_mul_f32_e32 v174, 0xbfb8aa3b, v174
	v_mul_f32_e32 v1, 0xbfb8aa3b, v182
	v_mul_f32_e32 v169, 0xbfb8aa3b, v183
	v_pk_add_f32 v[182:183], v[18:19], v[130:131]
	v_exp_f32_e32 v174, v174
	v_mul_f32_e32 v182, 0xbfb8aa3b, v182
	v_exp_f32_e32 v182, v182
	v_exp_f32_e32 v1, v1
	v_exp_f32_e32 v169, v169
	v_add_f32_e32 v174, 1.0, v174
	v_add_f32_e32 v182, 1.0, v182
	v_rcp_f32_e32 v186, v182
	v_mul_f32_e32 v182, 0xbfb8aa3b, v183
	v_mul_f32_e32 v138, 0xbfb8aa3b, v138
	v_add_f32_e32 v1, 1.0, v1
	v_add_f32_e32 v169, 1.0, v169
	v_rcp_f32_e32 v184, v174
	v_mul_f32_e32 v174, 0xbfb8aa3b, v175
	v_exp_f32_e32 v182, v182
	v_exp_f32_e32 v138, v138
	v_rcp_f32_e32 v1, v1
	v_rcp_f32_e32 v169, v169
	v_exp_f32_e32 v174, v174
	v_add_f32_e32 v182, 1.0, v182
	v_pk_add_f32 v[142:143], v[14:15], v[142:143]
	v_add_f32_e32 v138, 1.0, v138
	v_add_f32_e32 v174, 1.0, v174
	v_rcp_f32_e32 v187, v182
	v_cvt_pk_bf16_f32 v182, v1, v169
	v_mul_f32_e32 v1, 0xbfb8aa3b, v142
	v_mul_f32_e32 v142, 0xbfb8aa3b, v143
	v_mul_f32_e32 v143, 0xbfb8aa3b, v144
	v_mul_f32_e32 v144, 0xbfb8aa3b, v145
	v_rcp_f32_e32 v145, v138
	v_mul_f32_e32 v138, 0xbfb8aa3b, v139
	v_rcp_f32_e32 v185, v174
	v_pk_add_f32 v[174:175], v[20:21], v[132:133]
	v_exp_f32_e32 v138, v138
	v_mul_f32_e32 v174, 0xbfb8aa3b, v174
	v_mul_f32_e32 v175, 0xbfb8aa3b, v175
	v_exp_f32_e32 v174, v174
	v_exp_f32_e32 v175, v175
	v_pk_add_f32 v[140:141], v[12:13], v[140:141]
	v_add_f32_e32 v138, 1.0, v138
	v_rcp_f32_e32 v169, v138
	v_mul_f32_e32 v138, 0xbfb8aa3b, v140
	v_add_f32_e32 v174, 1.0, v174
	v_add_f32_e32 v175, 1.0, v175
	v_exp_f32_e32 v138, v138
	v_rcp_f32_e32 v174, v174
	v_rcp_f32_e32 v175, v175
	v_exp_f32_e32 v1, v1
	v_exp_f32_e32 v142, v142
	v_add_f32_e32 v138, 1.0, v138
	v_pk_add_f32 v[130:131], v[2:3], v[130:131]
	v_cvt_pk_bf16_f32 v183, v184, v185
	v_cvt_pk_bf16_f32 v185, v174, v175
	v_rcp_f32_e32 v174, v138
	v_mul_f32_e32 v138, 0xbfb8aa3b, v141
	v_mul_f32_e32 v130, 0xbfb8aa3b, v130
	v_add_f32_e32 v1, 1.0, v1
	v_add_f32_e32 v142, 1.0, v142
	v_exp_f32_e32 v138, v138
	v_exp_f32_e32 v130, v130
	v_rcp_f32_e32 v1, v1
	v_rcp_f32_e32 v142, v142
	v_exp_f32_e32 v143, v143
	v_exp_f32_e32 v144, v144
	v_add_f32_e32 v138, 1.0, v138
	v_pk_add_f32 v[136:137], v[8:9], v[136:137]
	v_pk_add_f32 v[134:135], v[6:7], v[134:135]
	v_add_f32_e32 v130, 1.0, v130
	v_add_f32_e32 v143, 1.0, v143
	v_add_f32_e32 v144, 1.0, v144
	v_rcp_f32_e32 v141, v138
	v_cvt_pk_bf16_f32 v138, v1, v142
	v_mul_f32_e32 v1, 0xbfb8aa3b, v134
	v_mul_f32_e32 v134, 0xbfb8aa3b, v135
	v_mul_f32_e32 v135, 0xbfb8aa3b, v136
	v_mul_f32_e32 v136, 0xbfb8aa3b, v137
	v_rcp_f32_e32 v137, v130
	v_mul_f32_e32 v130, 0xbfb8aa3b, v131
	v_rcp_f32_e32 v143, v143
	v_rcp_f32_e32 v144, v144
	v_exp_f32_e32 v130, v130
	v_cvt_pk_bf16_f32 v184, v186, v187
	s_mov_b64 s[0:1], 0xb0000
	global_store_dwordx4 v[172:173], v[182:185], off offset:256 nt
	v_lshl_add_u64 v[172:173], v[170:171], 0, s[0:1]
	s_mov_b32 s0, 0xb0000
	v_add_co_u32_e32 v142, vcc, s0, v170
	v_cvt_pk_bf16_f32 v139, v143, v144
	v_cvt_pk_bf16_f32 v140, v145, v169
	v_cvt_pk_bf16_f32 v141, v174, v141
	v_addc_co_u32_e32 v143, vcc, 0, v171, vcc
	v_pk_add_f32 v[132:133], v[4:5], v[132:133]
	v_add_f32_e32 v130, 1.0, v130
	global_store_dwordx4 v[142:143], v[138:141], off nt
	v_exp_f32_e32 v1, v1
	v_exp_f32_e32 v134, v134
	v_rcp_f32_e32 v138, v130
	v_mul_f32_e32 v130, 0xbfb8aa3b, v132
	v_exp_f32_e32 v130, v130
	v_exp_f32_e32 v135, v135
	v_exp_f32_e32 v136, v136
	v_add_f32_e32 v1, 1.0, v1
	v_add_f32_e32 v130, 1.0, v130
	v_rcp_f32_e32 v139, v130
	v_mul_f32_e32 v130, 0xbfb8aa3b, v133
	v_exp_f32_e32 v130, v130
	v_add_f32_e32 v134, 1.0, v134
	v_add_f32_e32 v135, 1.0, v135
	v_add_f32_e32 v136, 1.0, v136
	v_add_f32_e32 v130, 1.0, v130
	v_rcp_f32_e32 v1, v1
	v_rcp_f32_e32 v134, v134
	v_rcp_f32_e32 v135, v135
	v_rcp_f32_e32 v136, v136
	v_rcp_f32_e32 v133, v130
	v_cvt_pk_bf16_f32 v130, v1, v134
	v_cvt_pk_bf16_f32 v132, v137, v138
	v_cvt_pk_bf16_f32 v131, v135, v136
	v_cvt_pk_bf16_f32 v133, v139, v133
	global_store_dwordx4 v[172:173], v[130:133], off offset:256 nt

; __device__ __forceinline__ u32x4 pack8(const f32x4 a, const f32x4 b) { u32x4 w; w.x = cvt_pk_bf16(a[0], a[1]); w.y = cvt_pk_bf16(a[2], a[3]); w.z = cvt_pk_bf16(b[0], b[1]); w.w = cvt_pk_bf16(b[2], b[3]); return w; }
; __device__ __forceinline__ f32x4 silu4_new(const f32x4 v) { return v * sigm4_new(v); }
; #define EPI_ROWLOOP _Pragma("unroll") for (int ai = 0; ai < 2; ++ai) _Pragma("unroll") for (int m = 0; m < 4; ++m)
;     __device__ __forceinline__ void operator()(const f32x4 (&acc)[2][2][4][2], const Unit& u, int wr, int wc, int fr, int fq) const {
;         const int row0 = u.pm * BM + wr * 64 + fr, c0 = u.pn * 128 + wc * 32 + 8 * fq;
;         EPI_ROWLOOP { const int r = row0 + ai * HALF + m * 16;
;             *(u32x4*)(HID + (size_t)r * ldh + c0) = pack8(silu4_new(acc[ai][0][m][0]) * acc[ai][1][m][0], silu4_new(acc[ai][0][m][1]) * acc[ai][1][m][1]); }
;     }
.LBB0_1024:
	v_mul_f32_e32 v151, 0xbfb8aa3b, v124
	v_exp_f32_e32 v151, v151
	v_mul_f32_e32 v153, 0xbfb8aa3b, v125
	v_exp_f32_e32 v155, v153
	v_lshl_or_b32 v152, s67, 7, v146
	v_add_f32_e32 v151, 1.0, v151
	v_rcp_f32_e32 v154, v151
	v_add_f32_e32 v151, 1.0, v155
	v_mul_f32_e32 v155, 0xbfb8aa3b, v126
	v_exp_f32_e32 v156, v155
	v_mul_f32_e32 v155, 0xbfb8aa3b, v127
	v_exp_f32_e32 v157, v155
	v_rcp_f32_e32 v155, v151
	v_add_f32_e32 v151, 1.0, v156
	v_rcp_f32_e32 v156, v151
	v_add_f32_e32 v151, 1.0, v157
	v_rcp_f32_e32 v157, v151
	v_mul_f32_e32 v151, 0xbfb8aa3b, v116
	v_pk_mul_f32 v[124:125], v[124:125], v[154:155]
	v_exp_f32_e32 v151, v151
	v_mul_f32_e32 v154, 0xbfb8aa3b, v117
	v_exp_f32_e32 v155, v154
	v_pk_mul_f32 v[126:127], v[126:127], v[156:157]
	v_add_f32_e32 v151, 1.0, v151
	v_rcp_f32_e32 v154, v151
	v_add_f32_e32 v151, 1.0, v155
	v_mul_f32_e32 v155, 0xbfb8aa3b, v118
	v_exp_f32_e32 v156, v155
	v_mul_f32_e32 v155, 0xbfb8aa3b, v119
	v_exp_f32_e32 v157, v155
	v_rcp_f32_e32 v155, v151
	v_add_f32_e32 v151, 1.0, v156
	v_rcp_f32_e32 v156, v151
	v_add_f32_e32 v151, 1.0, v157
	v_rcp_f32_e32 v157, v151
	v_pk_mul_f32 v[116:117], v[116:117], v[154:155]
	v_lshl_add_u32 v150, s66, 8, v144
	v_pk_mul_f32 v[112:113], v[112:113], v[116:117]
	v_pk_mul_f32 v[118:119], v[118:119], v[156:157]
	v_ashrrev_i32_e32 v153, 31, v152
	v_pk_mul_f32 v[120:121], v[120:121], v[124:125]
	v_pk_mul_f32 v[114:115], v[114:115], v[118:119]
	v_cvt_pk_bf16_f32 v118, v112, v113
	v_mov_b64_e32 v[112:113], s[24:25]
	v_pk_mul_f32 v[122:123], v[122:123], v[126:127]
	v_cvt_pk_bf16_f32 v116, v120, v121
	v_cvt_pk_bf16_f32 v119, v114, v115
	v_mad_i64_i32 v[120:121], s[42:43], v150, s63, v[112:113]
	v_lshlrev_b64 v[114:115], 1, v[152:153]
	v_cvt_pk_bf16_f32 v117, v122, v123
	v_lshl_add_u64 v[120:121], v[120:121], 0, v[114:115]
	global_store_dwordx4 v[120:121], v[116:119], off nt
	v_or_b32_e32 v120, 16, v150
	s_and_b64 vcc, exec, s[6:7]
	v_mul_f32_e32 v116, 0xbfb8aa3b, v108
	v_mul_f32_e32 v117, 0xbfb8aa3b, v109
	v_mul_f32_e32 v118, 0xbfb8aa3b, v110
	v_mul_f32_e32 v119, 0xbfb8aa3b, v111
	v_exp_f32_e32 v116, v116
	v_exp_f32_e32 v117, v117
	v_exp_f32_e32 v118, v118
	v_exp_f32_e32 v119, v119
	v_add_f32_e32 v116, 1.0, v116
	v_add_f32_e32 v117, 1.0, v117
	v_add_f32_e32 v118, 1.0, v118
	v_add_f32_e32 v119, 1.0, v119
	v_rcp_f32_e32 v116, v116
	v_rcp_f32_e32 v117, v117
	v_rcp_f32_e32 v118, v118
	v_rcp_f32_e32 v119, v119
	s_mov_b64 s[6:7], -1
	v_pk_mul_f32 v[108:109], v[108:109], v[116:117]
	v_mul_f32_e32 v116, 0xbfb8aa3b, v100
	v_mul_f32_e32 v117, 0xbfb8aa3b, v101
	v_pk_mul_f32 v[110:111], v[110:111], v[118:119]
	v_mul_f32_e32 v118, 0xbfb8aa3b, v102
	v_mul_f32_e32 v119, 0xbfb8aa3b, v103
	v_exp_f32_e32 v116, v116
	v_exp_f32_e32 v117, v117
	v_exp_f32_e32 v118, v118
	v_exp_f32_e32 v119, v119
	v_add_f32_e32 v116, 1.0, v116
	v_add_f32_e32 v117, 1.0, v117
	v_add_f32_e32 v118, 1.0, v118
	v_add_f32_e32 v119, 1.0, v119
	v_rcp_f32_e32 v116, v116
	v_rcp_f32_e32 v117, v117
	v_rcp_f32_e32 v118, v118
	v_rcp_f32_e32 v119, v119
	v_pk_mul_f32 v[106:107], v[106:107], v[110:111]
	v_pk_mul_f32 v[100:101], v[100:101], v[116:117]
	v_pk_mul_f32 v[104:105], v[104:105], v[108:109]
	v_pk_mul_f32 v[102:103], v[102:103], v[118:119]
	s_nop 0
	v_pk_mul_f32 v[102:103], v[98:99], v[102:103]
	v_pk_mul_f32 v[98:99], v[96:97], v[100:101]
	v_mad_i64_i32 v[100:101], s[42:43], v120, s63, v[112:113]
	v_cvt_pk_bf16_f32 v96, v104, v105
	v_cvt_pk_bf16_f32 v97, v106, v107
	v_cvt_pk_bf16_f32 v98, v98, v99
	v_cvt_pk_bf16_f32 v99, v102, v103
	v_lshl_add_u64 v[100:101], v[100:101], 0, v[114:115]
	global_store_dwordx4 v[100:101], v[96:99], off nt
	v_or_b32_e32 v100, 32, v150
	s_nop 0
	v_mul_f32_e32 v96, 0xbfb8aa3b, v92
	v_mul_f32_e32 v97, 0xbfb8aa3b, v93
	v_mul_f32_e32 v98, 0xbfb8aa3b, v94
	v_mul_f32_e32 v99, 0xbfb8aa3b, v95
	v_exp_f32_e32 v96, v96
	v_exp_f32_e32 v97, v97
	v_exp_f32_e32 v98, v98
	v_exp_f32_e32 v99, v99
	v_add_f32_e32 v96, 1.0, v96
	v_add_f32_e32 v97, 1.0, v97
	v_add_f32_e32 v98, 1.0, v98
	v_add_f32_e32 v99, 1.0, v99
	v_rcp_f32_e32 v96, v96
	v_rcp_f32_e32 v97, v97
	v_rcp_f32_e32 v98, v98
	v_rcp_f32_e32 v99, v99
	v_pk_mul_f32 v[92:93], v[92:93], v[96:97]
	v_mul_f32_e32 v96, 0xbfb8aa3b, v84
	v_mul_f32_e32 v97, 0xbfb8aa3b, v85
	v_pk_mul_f32 v[94:95], v[94:95], v[98:99]
	v_mul_f32_e32 v98, 0xbfb8aa3b, v86
	v_mul_f32_e32 v99, 0xbfb8aa3b, v87
	v_exp_f32_e32 v96, v96
	v_exp_f32_e32 v97, v97
	v_exp_f32_e32 v98, v98
	v_exp_f32_e32 v99, v99
	v_add_f32_e32 v96, 1.0, v96
	v_add_f32_e32 v97, 1.0, v97
	v_add_f32_e32 v98, 1.0, v98
	v_add_f32_e32 v99, 1.0, v99
	v_rcp_f32_e32 v96, v96
	v_rcp_f32_e32 v97, v97
	v_rcp_f32_e32 v98, v98
	v_rcp_f32_e32 v99, v99
	v_pk_mul_f32 v[90:91], v[90:91], v[94:95]
	v_pk_mul_f32 v[84:85], v[84:85], v[96:97]
	v_pk_mul_f32 v[88:89], v[88:89], v[92:93]
	v_pk_mul_f32 v[86:87], v[86:87], v[98:99]
	s_nop 0
	v_pk_mul_f32 v[86:87], v[82:83], v[86:87]
	v_pk_mul_f32 v[82:83], v[80:81], v[84:85]
	v_mad_i64_i32 v[84:85], s[42:43], v100, s63, v[112:113]
	v_cvt_pk_bf16_f32 v80, v88, v89
	v_cvt_pk_bf16_f32 v81, v90, v91
	v_cvt_pk_bf16_f32 v82, v82, v83
	v_cvt_pk_bf16_f32 v83, v86, v87
	v_lshl_add_u64 v[84:85], v[84:85], 0, v[114:115]
	global_store_dwordx4 v[84:85], v[80:83], off nt
	v_or_b32_e32 v84, 48, v150
	s_nop 0
	v_mul_f32_e32 v80, 0xbfb8aa3b, v76
	v_mul_f32_e32 v81, 0xbfb8aa3b, v77
	v_mul_f32_e32 v82, 0xbfb8aa3b, v78
	v_mul_f32_e32 v83, 0xbfb8aa3b, v79
	v_exp_f32_e32 v80, v80
	v_exp_f32_e32 v81, v81
	v_exp_f32_e32 v82, v82
	v_exp_f32_e32 v83, v83
	v_add_f32_e32 v80, 1.0, v80
	v_add_f32_e32 v81, 1.0, v81
	v_add_f32_e32 v82, 1.0, v82
	v_add_f32_e32 v83, 1.0, v83
	v_rcp_f32_e32 v80, v80
	v_rcp_f32_e32 v81, v81
; __device__ __forceinline__ u32x4 pack8(const f32x4 a, const f32x4 b) { u32x4 w; w.x = cvt_pk_bf16(a[0], a[1]); w.y = cvt_pk_bf16(a[2], a[3]); w.z = cvt_pk_bf16(b[0], b[1]); w.w = cvt_pk_bf16(b[2], b[3]); return w; }
; __device__ __forceinline__ f32x4 silu4_new(const f32x4 v) { return v * sigm4_new(v); }
; #define EPI_ROWLOOP _Pragma("unroll") for (int ai = 0; ai < 2; ++ai) _Pragma("unroll") for (int m = 0; m < 4; ++m)
;     __device__ __forceinline__ void operator()(const f32x4 (&acc)[2][2][4][2], const Unit& u, int wr, int wc, int fr, int fq) const {
;         const int row0 = u.pm * BM + wr * 64 + fr, c0 = u.pn * 128 + wc * 32 + 8 * fq;
;         EPI_ROWLOOP { const int r = row0 + ai * HALF + m * 16;
;             *(u32x4*)(HID + (size_t)r * ldh + c0) = pack8(silu4_new(acc[ai][0][m][0]) * acc[ai][1][m][0], silu4_new(acc[ai][0][m][1]) * acc[ai][1][m][1]); }
;     }
	v_rcp_f32_e32 v82, v82
	v_rcp_f32_e32 v83, v83
	v_pk_mul_f32 v[76:77], v[76:77], v[80:81]
	v_mul_f32_e32 v80, 0xbfb8aa3b, v68
	v_mul_f32_e32 v81, 0xbfb8aa3b, v69
	v_pk_mul_f32 v[78:79], v[78:79], v[82:83]
	v_mul_f32_e32 v82, 0xbfb8aa3b, v70
	v_mul_f32_e32 v83, 0xbfb8aa3b, v71
	v_exp_f32_e32 v80, v80
	v_exp_f32_e32 v81, v81
	v_exp_f32_e32 v82, v82
	v_exp_f32_e32 v83, v83
	v_add_f32_e32 v80, 1.0, v80
	v_add_f32_e32 v81, 1.0, v81
	v_add_f32_e32 v82, 1.0, v82
	v_add_f32_e32 v83, 1.0, v83
	v_rcp_f32_e32 v80, v80
	v_rcp_f32_e32 v81, v81
	v_rcp_f32_e32 v82, v82
	v_rcp_f32_e32 v83, v83
	v_pk_mul_f32 v[74:75], v[74:75], v[78:79]
	v_pk_mul_f32 v[68:69], v[68:69], v[80:81]
	v_pk_mul_f32 v[72:73], v[72:73], v[76:77]
	v_pk_mul_f32 v[70:71], v[70:71], v[82:83]
	s_nop 0
	v_pk_mul_f32 v[70:71], v[66:67], v[70:71]
	v_pk_mul_f32 v[66:67], v[64:65], v[68:69]
	v_mad_i64_i32 v[68:69], s[42:43], v84, s63, v[112:113]
	v_cvt_pk_bf16_f32 v64, v72, v73
	v_cvt_pk_bf16_f32 v65, v74, v75
	v_cvt_pk_bf16_f32 v66, v66, v67
	v_cvt_pk_bf16_f32 v67, v70, v71
	v_lshl_add_u64 v[68:69], v[68:69], 0, v[114:115]
	global_store_dwordx4 v[68:69], v[64:67], off nt
	v_add_u32_e32 v68, 0x80, v150
	s_nop 0
	v_mul_f32_e32 v64, 0xbfb8aa3b, v60
	v_mul_f32_e32 v65, 0xbfb8aa3b, v61
	v_mul_f32_e32 v66, 0xbfb8aa3b, v62
	v_mul_f32_e32 v67, 0xbfb8aa3b, v63
	v_exp_f32_e32 v64, v64
	v_exp_f32_e32 v65, v65
	v_exp_f32_e32 v66, v66
	v_exp_f32_e32 v67, v67
	v_add_f32_e32 v64, 1.0, v64
	v_add_f32_e32 v65, 1.0, v65
	v_add_f32_e32 v66, 1.0, v66
	v_add_f32_e32 v67, 1.0, v67
	v_rcp_f32_e32 v64, v64
	v_rcp_f32_e32 v65, v65
	v_rcp_f32_e32 v66, v66
	v_rcp_f32_e32 v67, v67
	v_pk_mul_f32 v[60:61], v[60:61], v[64:65]
	v_mul_f32_e32 v64, 0xbfb8aa3b, v52
	v_mul_f32_e32 v65, 0xbfb8aa3b, v53
	v_pk_mul_f32 v[62:63], v[62:63], v[66:67]
	v_mul_f32_e32 v66, 0xbfb8aa3b, v54
	v_mul_f32_e32 v67, 0xbfb8aa3b, v55
	v_exp_f32_e32 v64, v64
	v_exp_f32_e32 v65, v65
	v_exp_f32_e32 v66, v66
	v_exp_f32_e32 v67, v67
	v_add_f32_e32 v64, 1.0, v64
	v_add_f32_e32 v65, 1.0, v65
	v_add_f32_e32 v66, 1.0, v66
	v_add_f32_e32 v67, 1.0, v67
	v_rcp_f32_e32 v64, v64
	v_rcp_f32_e32 v65, v65
	v_rcp_f32_e32 v66, v66
	v_rcp_f32_e32 v67, v67
	v_pk_mul_f32 v[58:59], v[58:59], v[62:63]
	v_pk_mul_f32 v[52:53], v[52:53], v[64:65]
	v_pk_mul_f32 v[56:57], v[56:57], v[60:61]
	v_pk_mul_f32 v[54:55], v[54:55], v[66:67]
	s_nop 0
	v_pk_mul_f32 v[54:55], v[50:51], v[54:55]
	v_pk_mul_f32 v[50:51], v[48:49], v[52:53]
	v_mad_i64_i32 v[52:53], s[42:43], v68, s63, v[112:113]
	v_cvt_pk_bf16_f32 v48, v56, v57
	v_cvt_pk_bf16_f32 v49, v58, v59
	v_cvt_pk_bf16_f32 v50, v50, v51
	v_cvt_pk_bf16_f32 v51, v54, v55
	v_lshl_add_u64 v[52:53], v[52:53], 0, v[114:115]
	global_store_dwordx4 v[52:53], v[48:51], off nt
	v_add_u32_e32 v52, 0x90, v150
	s_nop 0
	v_mul_f32_e32 v48, 0xbfb8aa3b, v44
	v_mul_f32_e32 v49, 0xbfb8aa3b, v45
	v_mul_f32_e32 v50, 0xbfb8aa3b, v46
	v_mul_f32_e32 v51, 0xbfb8aa3b, v47
	v_exp_f32_e32 v48, v48
	v_exp_f32_e32 v49, v49
	v_exp_f32_e32 v50, v50
	v_exp_f32_e32 v51, v51
	v_add_f32_e32 v48, 1.0, v48
	v_add_f32_e32 v49, 1.0, v49
	v_add_f32_e32 v50, 1.0, v50
	v_add_f32_e32 v51, 1.0, v51
	v_rcp_f32_e32 v48, v48
	v_rcp_f32_e32 v49, v49
	v_rcp_f32_e32 v50, v50
	v_rcp_f32_e32 v51, v51
	v_pk_mul_f32 v[44:45], v[44:45], v[48:49]
	v_mul_f32_e32 v48, 0xbfb8aa3b, v36
	v_mul_f32_e32 v49, 0xbfb8aa3b, v37
	v_pk_mul_f32 v[46:47], v[46:47], v[50:51]
	v_mul_f32_e32 v50, 0xbfb8aa3b, v38
	v_mul_f32_e32 v51, 0xbfb8aa3b, v39
	v_exp_f32_e32 v48, v48
	v_exp_f32_e32 v49, v49
	v_exp_f32_e32 v50, v50
	v_exp_f32_e32 v51, v51
	v_add_f32_e32 v48, 1.0, v48
	v_add_f32_e32 v49, 1.0, v49
	v_add_f32_e32 v50, 1.0, v50
	v_add_f32_e32 v51, 1.0, v51
	v_rcp_f32_e32 v48, v48
	v_rcp_f32_e32 v49, v49
	v_rcp_f32_e32 v50, v50
	v_rcp_f32_e32 v51, v51
; __device__ __forceinline__ u32x4 pack8(const f32x4 a, const f32x4 b) { u32x4 w; w.x = cvt_pk_bf16(a[0], a[1]); w.y = cvt_pk_bf16(a[2], a[3]); w.z = cvt_pk_bf16(b[0], b[1]); w.w = cvt_pk_bf16(b[2], b[3]); return w; }
; __device__ __forceinline__ f32x4 silu4_new(const f32x4 v) { return v * sigm4_new(v); }
; #define EPI_ROWLOOP _Pragma("unroll") for (int ai = 0; ai < 2; ++ai) _Pragma("unroll") for (int m = 0; m < 4; ++m)
;     __device__ __forceinline__ void operator()(const f32x4 (&acc)[2][2][4][2], const Unit& u, int wr, int wc, int fr, int fq) const {
;         const int row0 = u.pm * BM + wr * 64 + fr, c0 = u.pn * 128 + wc * 32 + 8 * fq;
;         EPI_ROWLOOP { const int r = row0 + ai * HALF + m * 16;
;             *(u32x4*)(HID + (size_t)r * ldh + c0) = pack8(silu4_new(acc[ai][0][m][0]) * acc[ai][1][m][0], silu4_new(acc[ai][0][m][1]) * acc[ai][1][m][1]); }
;     }
	v_pk_mul_f32 v[42:43], v[42:43], v[46:47]
	v_pk_mul_f32 v[36:37], v[36:37], v[48:49]
	v_pk_mul_f32 v[40:41], v[40:41], v[44:45]
	v_pk_mul_f32 v[38:39], v[38:39], v[50:51]
	s_nop 0
	v_pk_mul_f32 v[38:39], v[34:35], v[38:39]
	v_pk_mul_f32 v[34:35], v[32:33], v[36:37]
	v_mad_i64_i32 v[36:37], s[42:43], v52, s63, v[112:113]
	v_cvt_pk_bf16_f32 v32, v40, v41
	v_cvt_pk_bf16_f32 v33, v42, v43
	v_cvt_pk_bf16_f32 v34, v34, v35
	v_cvt_pk_bf16_f32 v35, v38, v39
	v_lshl_add_u64 v[36:37], v[36:37], 0, v[114:115]
	global_store_dwordx4 v[36:37], v[32:35], off nt
	v_add_u32_e32 v36, 0xa0, v150
	s_nop 0
	v_mul_f32_e32 v32, 0xbfb8aa3b, v28
	v_mul_f32_e32 v33, 0xbfb8aa3b, v29
	v_mul_f32_e32 v34, 0xbfb8aa3b, v30
	v_mul_f32_e32 v35, 0xbfb8aa3b, v31
	v_exp_f32_e32 v32, v32
	v_exp_f32_e32 v33, v33
	v_exp_f32_e32 v34, v34
	v_exp_f32_e32 v35, v35
	v_add_f32_e32 v32, 1.0, v32
	v_add_f32_e32 v33, 1.0, v33
	v_add_f32_e32 v34, 1.0, v34
	v_add_f32_e32 v35, 1.0, v35
	v_rcp_f32_e32 v32, v32
	v_rcp_f32_e32 v33, v33
	v_rcp_f32_e32 v34, v34
	v_rcp_f32_e32 v35, v35
	v_pk_mul_f32 v[28:29], v[28:29], v[32:33]
	v_mul_f32_e32 v32, 0xbfb8aa3b, v20
	v_mul_f32_e32 v33, 0xbfb8aa3b, v21
	v_pk_mul_f32 v[30:31], v[30:31], v[34:35]
	v_mul_f32_e32 v34, 0xbfb8aa3b, v22
	v_mul_f32_e32 v35, 0xbfb8aa3b, v23
	v_exp_f32_e32 v32, v32
	v_exp_f32_e32 v33, v33
	v_exp_f32_e32 v34, v34
	v_exp_f32_e32 v35, v35
	v_add_f32_e32 v32, 1.0, v32
	v_add_f32_e32 v33, 1.0, v33
	v_add_f32_e32 v34, 1.0, v34
	v_add_f32_e32 v35, 1.0, v35
	v_rcp_f32_e32 v32, v32
	v_rcp_f32_e32 v33, v33
	v_rcp_f32_e32 v34, v34
	v_rcp_f32_e32 v35, v35
	v_pk_mul_f32 v[26:27], v[26:27], v[30:31]
	v_pk_mul_f32 v[20:21], v[20:21], v[32:33]
	v_pk_mul_f32 v[24:25], v[24:25], v[28:29]
	v_pk_mul_f32 v[22:23], v[22:23], v[34:35]
	s_nop 0
	v_pk_mul_f32 v[22:23], v[18:19], v[22:23]
	v_pk_mul_f32 v[18:19], v[16:17], v[20:21]
	v_mad_i64_i32 v[20:21], s[42:43], v36, s63, v[112:113]
	v_cvt_pk_bf16_f32 v16, v24, v25
	v_cvt_pk_bf16_f32 v17, v26, v27
	v_cvt_pk_bf16_f32 v18, v18, v19
	v_cvt_pk_bf16_f32 v19, v22, v23
	v_lshl_add_u64 v[20:21], v[20:21], 0, v[114:115]
	global_store_dwordx4 v[20:21], v[16:19], off nt
	v_add_u32_e32 v20, 0xb0, v150
	s_nop 0
	v_mul_f32_e32 v16, 0xbfb8aa3b, v12
	v_mul_f32_e32 v17, 0xbfb8aa3b, v13
	v_mul_f32_e32 v18, 0xbfb8aa3b, v14
	v_mul_f32_e32 v19, 0xbfb8aa3b, v15
	v_exp_f32_e32 v16, v16
	v_exp_f32_e32 v17, v17
	v_exp_f32_e32 v18, v18
	v_exp_f32_e32 v19, v19
	v_add_f32_e32 v16, 1.0, v16
	v_add_f32_e32 v17, 1.0, v17
	v_add_f32_e32 v18, 1.0, v18
	v_add_f32_e32 v19, 1.0, v19
	v_rcp_f32_e32 v16, v16
	v_rcp_f32_e32 v17, v17
	v_rcp_f32_e32 v18, v18
	v_rcp_f32_e32 v19, v19
	v_pk_mul_f32 v[12:13], v[12:13], v[16:17]
	v_mul_f32_e32 v16, 0xbfb8aa3b, v4
	v_mul_f32_e32 v17, 0xbfb8aa3b, v5
	v_pk_mul_f32 v[14:15], v[14:15], v[18:19]
	v_mul_f32_e32 v18, 0xbfb8aa3b, v6
	v_mul_f32_e32 v19, 0xbfb8aa3b, v7
	v_exp_f32_e32 v16, v16
	v_exp_f32_e32 v17, v17
	v_exp_f32_e32 v18, v18
	v_exp_f32_e32 v19, v19
	v_add_f32_e32 v16, 1.0, v16
	v_add_f32_e32 v17, 1.0, v17
	v_add_f32_e32 v18, 1.0, v18
	v_add_f32_e32 v19, 1.0, v19
	v_rcp_f32_e32 v16, v16
	v_rcp_f32_e32 v17, v17
	v_rcp_f32_e32 v18, v18
	v_rcp_f32_e32 v19, v19
	v_pk_mul_f32 v[10:11], v[10:11], v[14:15]
	v_pk_mul_f32 v[4:5], v[4:5], v[16:17]
	v_pk_mul_f32 v[8:9], v[8:9], v[12:13]
	v_pk_mul_f32 v[6:7], v[6:7], v[18:19]
	s_nop 0
	v_pk_mul_f32 v[6:7], v[2:3], v[6:7]
	v_pk_mul_f32 v[2:3], v[0:1], v[4:5]
	v_mad_i64_i32 v[4:5], s[42:43], v20, s63, v[112:113]
	v_cvt_pk_bf16_f32 v0, v8, v9
	v_cvt_pk_bf16_f32 v1, v10, v11
	v_cvt_pk_bf16_f32 v2, v2, v3
	v_cvt_pk_bf16_f32 v3, v6, v7
	v_lshl_add_u64 v[4:5], v[4:5], 0, v[114:115]
	global_store_dwordx4 v[4:5], v[0:3], off nt
	s_cbranch_vccnz .LBB0_1012
	s_andn2_b64 vcc, exec, s[14:15]
	s_cbranch_vccnz .LBB0_1011
	s_barrier
	s_branch .LBB0_1011
